# gemm_f32 k-loop: two staging register sets, loads 3 k-tiles ahead, no vmcnt(0) before the barrier
# speedup vs baseline: 1.0054x; 1.0004x over previous
; #define BIDX (opaque_bid() * 2 + HALF_)
; __device__ __forceinline__ void phase_cmp2(const Params& p, int l, u16* smem) {
;   (void)l;
;   u16* kcmp = (u16*)(p.ws + OFF_KCMP);
;   u16* vcmpT = (u16*)(p.ws + OFF_VCMP);
;   const int tid = TIDX;
;   const int lane = tid & 63, wave = tid >> 6;
;   const int wm = wave >> 1, wn = wave & 1;
;   for (int it = BIDX; it < 32; it += VGRID) {
;     const int m = it >> 4, mt = it & 15;
;     const u16* A = (const u16*)(p.ws + OFF_HC) + (size_t)m * 2048 * 256;
;     const u16* Bt = (const u16*)(p.ws + W_C2) + (size_t)m * 64 * 256;
;     f32x4 acc[4][2];
; #pragma unroll
;     for (int i = 0; i < 4; ++i)
; #pragma unroll
;       for (int j = 0; j < 2; ++j) acc[i][j] = (f32x4){0.f, 0.f, 0.f, 0.f};
;     gemm_acc<2>(acc, A, 256, Bt, 256, 0, 256, mt * 128, 0, smem);
.LBB0_190:
	s_and_b64 vcc, exec, s[0:1]
	s_cbranch_vccz .LBB0_475
	s_mov_b64 s[0:1], 0
	v_writelane_b32 v254, s0, 62
	s_mov_b64 s[10:11], -1
	s_cmp_gt_i32 s82, 3
	v_writelane_b32 v254, s1, 63
	s_mov_b64 s[0:1], 0
	s_cbranch_scc0 .LBB0_427
	s_cmp_gt_i32 s82, 4
	s_cbranch_scc0 .LBB0_393
	s_cmp_gt_i32 s82, 5
	s_mov_b64 s[0:1], -1
	s_cbranch_scc0 .LBB0_392
	s_waitcnt vmcnt(15)
	v_mov_b32_e32 v2, v175
	v_readlane_b32 s0, v252, 0
	v_mov_b32_e32 v0, v175
	s_lshl_b32 s10, s0, 1
	v_readfirstlane_b32 s1, v0
	s_ashr_i32 s1, s1, 8
	s_add_i32 s22, s1, s10
	s_cmp_gt_i32 s22, 31
	s_cbranch_scc1 .LBB0_373
	v_lshrrev_b32_e32 v4, 2, v2
	v_lshrrev_b32_e32 v0, 1, v2
	s_waitcnt vmcnt(10)
	v_and_b32_e32 v50, 15, v2
	v_and_b32_e32 v4, 12, v4
	v_and_b32_e32 v3, 32, v0
	v_and_or_b32 v51, v0, 64, v4
	v_lshlrev_b32_e32 v4, 4, v50
	v_readlane_b32 s10, v252, 56
	v_and_b32_e32 v52, 7, v2
	v_lshl_or_b32 v0, v3, 7, v4
	v_readlane_b32 s11, v252, 57
	v_lshlrev_b32_e32 v54, 1, v52
	v_readlane_b32 s12, v252, 58
	s_waitcnt vmcnt(4)
	v_lshl_add_u64 v[34:35], s[10:11], 0, v[0:1]
	v_and_or_b32 v0, v2, 8, v3
	v_lshl_or_b32 v0, v0, 5, v54
	v_readlane_b32 s13, v252, 59
	v_bfe_u32 v53, v2, 6, 1
	s_lshl_b32 s0, s0, 8
	v_lshl_add_u64 v[36:37], s[12:13], 0, v[0:1]
	v_lshlrev_b32_e32 v0, 1, v2
	v_or_b32_e32 v2, 16, v3
	v_and_b32_e32 v56, 16, v0
	v_or_b32_e32 v5, v2, v50
	v_lshl_or_b32 v0, v2, 7, v4
	v_lshl_add_u64 v[38:39], s[10:11], 0, v[0:1]
	v_and_or_b32 v0, v5, 24, v3
	v_lshl_or_b32 v0, v0, 5, v54
	v_lshl_add_u64 v[40:41], s[12:13], 0, v[0:1]
	v_lshlrev_b32_e32 v0, 1, v5
	s_mov_b64 s[10:11], 0xe70e
	s_mov_b64 s[12:13], 0xf8f0
	s_lshl_b32 s1, s1, 7
	v_lshrrev_b32_e32 v55, 3, v3
	v_lshrrev_b32_e32 v57, 3, v2
	v_and_b32_e32 v58, 48, v0
	v_lshl_add_u64 v[42:43], v[34:35], 0, s[10:11]
	v_lshl_add_u64 v[44:45], v[36:37], 0, s[12:13]
	v_lshl_add_u64 v[46:47], v[38:39], 0, s[10:11]
	v_lshl_add_u64 v[48:49], v[40:41], 0, s[12:13]
	s_add_i32 s23, s0, s1
	s_branch .LBB0_197
.Ltramp7:
	s_branch .LBB0_7
.LBB0_196:
	s_or_b64 exec, exec, s[0:1]
	v_readlane_b32 s0, v254, 36
	s_add_i32 s22, s22, s96
	s_add_i32 s23, s23, s0
	s_cmp_lt_i32 s22, 32
	s_cbranch_scc0 .LBB0_373

; #define ZERO_ACC8(acc, NJ_)                             \
;   _Pragma("unroll") for (int i_ = 0; i_ < 8; ++i_)      \
;   _Pragma("unroll") for (int j_ = 0; j_ < (NJ_); ++j_) { acc[i_][j_] = (f32x4){0.f, 0.f, 0.f, 0.f}; }
; template <int MI, int NJ> ...
;     ...
;   const u16* Ag = A + (size_t)(row0 + lrow) * lda + kbeg + lkc * 8;
;   const u16* Bg = Bt + (size_t)(col0 + lrow) * ldb + kbeg + lkc * 8;
;   const size_t a64 = (size_t)64 * lda, b64 = (size_t)64 * ldb;
;   const int nk = (kend - kbeg) >> 6;
;   const long long nAoff = (long long)(nrow0 - row0) * lda + (nkbeg - kbeg);
;   const long long nBoff = (long long)(ncol0 - col0) * ldb + (nkbeg - kbeg);
;   u16* wa = sA + lrow * 64 + ((lkc ^ (lrow & 7)) * 8);
;   u16* wb = sB + lrow * 64 + ((lkc ^ (lrow & 7)) * 8);
;     ...
;   if (!pre) G8LOADP(Ag, Bg);
;   G8STORE(0);
;   {
;     const u16* ga_ = (1 < nk) ? Ag + 64 : Ag + nAoff;
;     const u16* gb_ = (1 < nk) ? Bg + 64 : Bg + nBoff;
;     G8LOADP(ga_, gb_);
;   }
;   __syncthreads();
; __device__ __forceinline__ void phase_gemm_f32(const u16* A, const u16* Bt, int K, u16* out, u16* smem,
;                                                volatile LAS unsigned* vb_) {
;     ...
;   for (int lt = vb >> 3; lt < 8 * 4; lt += step) {
;     const int nt = lt >> 3, mt = (vb & 7) * 8 + (lt & 7);
;     const int ltn = (lt + step < 8 * 4) ? lt + step : lt;
;     f32x4 acc[8][4];
;     ZERO_ACC8(acc, 4);
;     gemm8<8, 4>(acc, G8REGS_ARGS, pre, A, K, Bt, K, 0, K, mt * 256, nt * 256, ((vb & 7) * 8 + (ltn & 7)) * 256, (ltn >> 3) * 256, 0, smem, tid);
.LBB0_478:
	s_and_b32 s38, s37, 7
	s_or_b32 s23, s38, s22
	s_lshl_b32 s23, s23, 8
	s_lshl_b32 s36, s37, 5
	s_and_b32 s42, s36, 0xffffff00
	v_add_u32_e32 v0, s23, v184
	v_mad_i64_i32 v[22:23], s[40:41], v0, s10, 0
	v_add_u32_e32 v0, s42, v184
	v_lshl_add_u64 v[180:181], v[22:23], 1, v[176:177]
	v_mad_i64_i32 v[22:23], s[40:41], v0, s10, 0
	v_lshl_add_u64 v[182:183], v[22:23], 1, v[178:179]
	s_and_b64 vcc, exec, s[12:13]
	s_cbranch_vccnz .LBB0_480
	v_lshl_add_u64 v[242:243], v[180:181], 0, s[58:59]
	v_lshl_add_u64 v[244:245], v[242:243], 0, s[0:1]
	v_lshl_add_u64 v[246:247], v[244:245], 0, s[0:1]
	v_lshl_add_u64 v[248:249], v[182:183], 0, s[58:59]
	v_lshl_add_u64 v[250:251], v[248:249], 0, s[0:1]
	v_lshl_add_u64 v[228:229], v[250:251], 0, s[0:1]
	global_load_dwordx4 v[10:13], v[180:181], off
	global_load_dwordx4 v[2:5], v[242:243], off
	global_load_dwordx4 v[6:9], v[244:245], off
	global_load_dwordx4 v[14:17], v[246:247], off
	global_load_dwordx4 v[18:21], v[182:183], off
	global_load_dwordx4 v[42:45], v[248:249], off
	global_load_dwordx4 v[62:65], v[250:251], off
	global_load_dwordx4 v[74:77], v[228:229], off
	global_load_dwordx4 v[204:207], v[180:181], off offset:128
	global_load_dwordx4 v[208:211], v[242:243], off offset:128
	global_load_dwordx4 v[212:215], v[244:245], off offset:128
	global_load_dwordx4 v[216:219], v[246:247], off offset:128
	global_load_dwordx4 v[220:223], v[182:183], off offset:128
	global_load_dwordx4 v[224:227], v[248:249], off offset:128
	global_load_dwordx4 v[234:237], v[250:251], off offset:128
	global_load_dwordx4 v[238:241], v[228:229], off offset:128
	s_waitcnt vmcnt(8)
.LBB0_480:
	s_waitcnt vmcnt(16)
	ds_write_b128 v185, v[10:13]
	ds_write_b128 v185, v[2:5] offset:8192
	ds_write_b128 v185, v[6:9] offset:16384
	ds_write_b128 v185, v[14:17] offset:24576
	ds_write_b128 v186, v[18:21]
	ds_write_b128 v186, v[42:45] offset:8192
	ds_write_b128 v186, v[62:65] offset:16384
	ds_write_b128 v186, v[74:77] offset:24576
	v_lshl_add_u64 v[242:243], v[180:181], 0, s[58:59]
	v_lshl_add_u64 v[244:245], v[242:243], 0, s[0:1]
	v_lshl_add_u64 v[246:247], v[244:245], 0, s[0:1]
	v_lshl_add_u64 v[248:249], v[182:183], 0, s[58:59]
	v_lshl_add_u64 v[250:251], v[248:249], 0, s[0:1]
	v_lshl_add_u64 v[228:229], v[250:251], 0, s[0:1]
	global_load_dwordx4 v[10:13], v[180:181], off offset:256
	global_load_dwordx4 v[2:5], v[242:243], off offset:256
	global_load_dwordx4 v[6:9], v[244:245], off offset:256
	global_load_dwordx4 v[14:17], v[246:247], off offset:256
	global_load_dwordx4 v[18:21], v[182:183], off offset:256
	global_load_dwordx4 v[42:45], v[248:249], off offset:256
	global_load_dwordx4 v[62:65], v[250:251], off offset:256
	global_load_dwordx4 v[74:77], v[228:229], off offset:256
	s_add_i32 s36, s37, s70
	s_cmp_gt_i32 s36, 31
	s_cselect_b64 s[40:41], -1, 0
	s_cmp_lt_i32 s36, 32
	s_cselect_b32 s12, s36, s37
	s_and_b32 s13, s12, 7
	s_lshl_b32 s12, s12, 5
	s_and_b32 s37, s12, 0xffffff00
	s_sub_i32 s12, s13, s38
	s_lshl_b32 s13, s12, 8
	s_sub_i32 s38, s37, s42
	v_mov_b32_e32 v22, 0
	s_mul_hi_i32 s12, s13, s10
	s_mul_i32 s13, s13, s10
	s_mul_hi_i32 s37, s38, s10
	s_mul_i32 s38, s38, s10
	s_movk_i32 s39, 0xc0
	s_mov_b32 s43, 0
	s_mov_b32 s44, 0
	v_mov_b32_e32 v23, v22
	v_mov_b32_e32 v24, v22
	v_mov_b32_e32 v25, v22
	v_mov_b32_e32 v26, v22
	v_mov_b32_e32 v27, v22
	v_mov_b32_e32 v28, v22
	v_mov_b32_e32 v29, v22
	v_mov_b32_e32 v30, v22
	v_mov_b32_e32 v31, v22
	v_mov_b32_e32 v32, v22
	v_mov_b32_e32 v33, v22
	v_mov_b32_e32 v34, v22
	v_mov_b32_e32 v35, v22
	v_mov_b32_e32 v36, v22
	v_mov_b32_e32 v37, v22
	v_mov_b32_e32 v38, v22
	v_mov_b32_e32 v39, v22
	v_mov_b32_e32 v40, v22
	v_mov_b32_e32 v41, v22
	v_mov_b32_e32 v46, v22
	v_mov_b32_e32 v47, v22
	v_mov_b32_e32 v48, v22
	v_mov_b32_e32 v49, v22
	v_mov_b32_e32 v50, v22
	v_mov_b32_e32 v51, v22
	v_mov_b32_e32 v52, v22
	v_mov_b32_e32 v53, v22
	v_mov_b32_e32 v54, v22
	v_mov_b32_e32 v55, v22
	v_mov_b32_e32 v56, v22
	v_mov_b32_e32 v57, v22
	v_mov_b32_e32 v58, v22
	v_mov_b32_e32 v59, v22
	v_mov_b32_e32 v60, v22
	v_mov_b32_e32 v61, v22
	v_mov_b32_e32 v66, v22
	v_mov_b32_e32 v67, v22
	v_mov_b32_e32 v68, v22
	v_mov_b32_e32 v69, v22
	v_mov_b32_e32 v70, v22
	v_mov_b32_e32 v71, v22
	v_mov_b32_e32 v72, v22
	v_mov_b32_e32 v73, v22
	v_mov_b32_e32 v78, v22
	v_mov_b32_e32 v79, v22
	v_mov_b32_e32 v80, v22
	v_mov_b32_e32 v81, v22
	v_mov_b32_e32 v82, v22
	v_mov_b32_e32 v83, v22
	v_mov_b32_e32 v84, v22
	v_mov_b32_e32 v85, v22
	v_mov_b32_e32 v86, v22
	v_mov_b32_e32 v87, v22
	v_mov_b32_e32 v88, v22
	v_mov_b32_e32 v89, v22
	v_mov_b32_e32 v90, v22
	v_mov_b32_e32 v91, v22
	v_mov_b32_e32 v92, v22
	v_mov_b32_e32 v93, v22
	v_mov_b32_e32 v94, v22
	v_mov_b32_e32 v95, v22
	v_mov_b32_e32 v96, v22
	v_mov_b32_e32 v97, v22
	v_mov_b32_e32 v98, v22
	v_mov_b32_e32 v99, v22
	v_mov_b32_e32 v100, v22
	v_mov_b32_e32 v101, v22
	v_mov_b32_e32 v102, v22
	v_mov_b32_e32 v103, v22
	v_mov_b32_e32 v104, v22
	v_mov_b32_e32 v105, v22
	v_mov_b32_e32 v106, v22
	v_mov_b32_e32 v107, v22
	v_mov_b32_e32 v108, v22
	v_mov_b32_e32 v109, v22
	v_mov_b32_e32 v110, v22
	v_mov_b32_e32 v111, v22
	v_mov_b32_e32 v112, v22
	v_mov_b32_e32 v113, v22
	v_mov_b32_e32 v114, v22
	v_mov_b32_e32 v115, v22
	v_mov_b32_e32 v116, v22
	v_mov_b32_e32 v117, v22
	v_mov_b32_e32 v118, v22
	v_mov_b32_e32 v119, v22
	v_mov_b32_e32 v120, v22
	v_mov_b32_e32 v121, v22
	v_mov_b32_e32 v122, v22
	v_mov_b32_e32 v123, v22
	v_mov_b32_e32 v124, v22
	v_mov_b32_e32 v125, v22
	v_mov_b32_e32 v126, v22
	v_mov_b32_e32 v127, v22
	v_mov_b32_e32 v128, v22
	v_mov_b32_e32 v129, v22
	v_mov_b32_e32 v130, v22
	v_mov_b32_e32 v131, v22
	v_mov_b32_e32 v132, v22
	v_mov_b32_e32 v133, v22
	v_mov_b32_e32 v134, v22
	v_mov_b32_e32 v135, v22
	v_mov_b32_e32 v136, v22
	v_mov_b32_e32 v137, v22
	v_mov_b32_e32 v138, v22
	v_mov_b32_e32 v139, v22
	v_mov_b32_e32 v140, v22
	v_mov_b32_e32 v141, v22
	v_mov_b32_e32 v142, v22
	v_mov_b32_e32 v143, v22
	v_mov_b32_e32 v144, v22
	v_mov_b32_e32 v145, v22
	v_mov_b32_e32 v146, v22
	v_mov_b32_e32 v147, v22
	v_mov_b32_e32 v148, v22
	v_mov_b32_e32 v149, v22
	v_mov_b32_e32 v150, v22
	v_mov_b32_e32 v151, v22
	v_mov_b32_e32 v152, v22
	v_mov_b32_e32 v153, v22
	v_mov_b32_e32 v154, v22
	v_mov_b32_e32 v155, v22
	v_mov_b32_e32 v156, v22
	v_mov_b32_e32 v157, v22
	v_mov_b32_e32 v158, v22
	v_mov_b32_e32 v159, v22
	v_mov_b32_e32 v160, v22
	v_mov_b32_e32 v161, v22
	s_waitcnt lgkmcnt(0)
	s_barrier
; template <int MI, int NJ> ...
;     ...
;   for (int kt = 0; kt < nk; ++kt) {
;     const int buf = kt & 1;
;     {
;       G8STORE(buf ^ 1);
;       const u16* ga_ = (kt + 2 < nk) ? Ag + (kt + 2) * 64 : Ag + nAoff;
;       const u16* gb_ = (kt + 2 < nk) ? Bg + (kt + 2) * 64 : Bg + nBoff;
;       G8LOADP(ga_, gb_);
;     }
;     __builtin_amdgcn_sched_barrier(0);
;     __builtin_amdgcn_s_setprio(1);
;     const u16* a = ra_ + buf * AROWS * 64;
;     const u16* b = rb_ + buf * BROWS * 64;
; #pragma unroll
;     for (int ks = 0; ks < 2; ++ks) {
;       const u16* a_ = ks ? a + dsw : a;
;       const u16* b_ = ks ? b + dsw : b;
;       bf16x8 bfr[NJ];
; #pragma unroll
;       for (int j = 0; j < NJ; ++j) bfr[j] = *(const bf16x8*)(b_ + j * 16 * 64);
; #pragma unroll
;       for (int ih = 0; ih < MI / 4; ++ih) {
;         bf16x8 af[4];
; #pragma unroll
;         for (int i = 0; i < 4; ++i) af[i] = *(const bf16x8*)(a_ + (ih * 4 + i) * 16 * 64);
; #pragma unroll
;         for (int i = 0; i < 4; ++i)
; #pragma unroll
;           for (int j = 0; j < NJ; ++j) acc[ih * 4 + i][j] = mfma16(af[i], bfr[j], acc[ih * 4 + i][j]);
;       }
;     }
;     __builtin_amdgcn_s_setprio(0);
;     __builtin_amdgcn_sched_barrier(0);
;     __syncthreads();
;   }
.LBB0_481:
	s_and_b32 s45, s43, 0x4000
	s_xor_b32 s46, s45, 0x4000
	s_lshl_b32 s46, s46, 1
	v_add_u32_e32 v0, s46, v185
	v_add_u32_e32 v191, s46, v186
	s_add_i32 s46, s44, 3
	s_sub_i32 s48, s46, s21
	s_cmp_eq_u32 s48, 1
	s_cselect_b32 s48, 64, 0
	s_add_u32 s49, s13, s48
	s_addc_u32 s50, s12, 0
	s_add_u32 s51, s38, s48
	s_addc_u32 s52, s37, 0
	s_cmp_lt_u32 s46, s21
	s_cselect_b32 s47, 0, s50
	s_cselect_b32 s46, s39, s49
	s_cselect_b32 s53, 0, s52
	s_cselect_b32 s52, s39, s51
	s_waitcnt vmcnt(8)
	ds_write_b128 v0, v[204:207]
	ds_write_b128 v0, v[208:211] offset:8192
	ds_write_b128 v0, v[212:215] offset:16384
	ds_write_b128 v0, v[216:219] offset:24576
	ds_write_b128 v191, v[220:223]
	ds_write_b128 v191, v[224:227] offset:8192
	ds_write_b128 v191, v[234:237] offset:16384
	ds_write_b128 v191, v[238:241] offset:24576
	v_lshl_add_u64 v[242:243], s[46:47], 1, v[180:181]
	v_lshl_add_u64 v[248:249], s[52:53], 1, v[182:183]
	v_lshl_add_u64 v[244:245], v[242:243], 0, s[58:59]
	v_lshl_add_u64 v[250:251], v[248:249], 0, s[58:59]
	global_load_dwordx4 v[204:207], v[242:243], off
	v_lshl_add_u64 v[246:247], v[244:245], 0, s[0:1]
	global_load_dwordx4 v[208:211], v[244:245], off
	v_lshl_add_u64 v[244:245], v[246:247], 0, s[0:1]
	global_load_dwordx4 v[212:215], v[246:247], off
	v_lshl_add_u64 v[228:229], v[250:251], 0, s[0:1]
	global_load_dwordx4 v[216:219], v[244:245], off
	global_load_dwordx4 v[220:223], v[248:249], off
	v_lshl_add_u64 v[246:247], v[228:229], 0, s[0:1]
	global_load_dwordx4 v[224:227], v[250:251], off
	global_load_dwordx4 v[234:237], v[228:229], off
	global_load_dwordx4 v[238:241], v[246:247], off
	s_setprio 1
	s_lshl_b32 s45, s45, 1
	v_add_u32_e32 v0, s45, v187
	v_add_u32_e32 v191, s45, v188
	ds_read_b128 v[162:165], v0
	ds_read_b128 v[166:169], v191
	ds_read_b128 v[170:173], v191 offset:2048
	ds_read_b128 v[192:195], v191 offset:4096
	ds_read_b128 v[196:199], v191 offset:6144
	s_waitcnt lgkmcnt(3)
	v_mfma_f32_16x16x32_bf16 v[158:161], v[162:165], v[166:169], v[158:161]
	v_add_u32_e32 v191, v191, v190
	s_waitcnt lgkmcnt(2)
	v_mfma_f32_16x16x32_bf16 v[154:157], v[162:165], v[170:173], v[154:157]
	s_waitcnt lgkmcnt(1)
	v_mfma_f32_16x16x32_bf16 v[150:153], v[162:165], v[192:195], v[150:153]
	s_waitcnt lgkmcnt(0)
	v_mfma_f32_16x16x32_bf16 v[146:149], v[162:165], v[196:199], v[146:149]
	ds_read_b128 v[162:165], v0 offset:2048
	s_waitcnt lgkmcnt(0)
	v_mfma_f32_16x16x32_bf16 v[142:145], v[162:165], v[166:169], v[142:145]
	v_mfma_f32_16x16x32_bf16 v[138:141], v[162:165], v[170:173], v[138:141]
	v_mfma_f32_16x16x32_bf16 v[134:137], v[162:165], v[192:195], v[134:137]
	v_mfma_f32_16x16x32_bf16 v[130:133], v[162:165], v[196:199], v[130:133]
	ds_read_b128 v[162:165], v0 offset:4096
	s_waitcnt lgkmcnt(0)
	v_mfma_f32_16x16x32_bf16 v[126:129], v[162:165], v[166:169], v[126:129]
	v_mfma_f32_16x16x32_bf16 v[122:125], v[162:165], v[170:173], v[122:125]
	v_mfma_f32_16x16x32_bf16 v[118:121], v[162:165], v[192:195], v[118:121]
	v_mfma_f32_16x16x32_bf16 v[114:117], v[162:165], v[196:199], v[114:117]
	ds_read_b128 v[162:165], v0 offset:6144
	s_waitcnt lgkmcnt(0)
	v_mfma_f32_16x16x32_bf16 v[110:113], v[162:165], v[166:169], v[110:113]
	v_mfma_f32_16x16x32_bf16 v[106:109], v[162:165], v[170:173], v[106:109]
	v_mfma_f32_16x16x32_bf16 v[102:105], v[162:165], v[192:195], v[102:105]
	v_mfma_f32_16x16x32_bf16 v[98:101], v[162:165], v[196:199], v[98:101]
	ds_read_b128 v[162:165], v0 offset:8192
	s_waitcnt lgkmcnt(0)
	v_mfma_f32_16x16x32_bf16 v[94:97], v[162:165], v[166:169], v[94:97]
	v_mfma_f32_16x16x32_bf16 v[90:93], v[162:165], v[170:173], v[90:93]
	v_mfma_f32_16x16x32_bf16 v[86:89], v[162:165], v[192:195], v[86:89]
	v_mfma_f32_16x16x32_bf16 v[82:85], v[162:165], v[196:199], v[82:85]
	ds_read_b128 v[162:165], v0 offset:10240
	s_waitcnt lgkmcnt(0)
	v_mfma_f32_16x16x32_bf16 v[78:81], v[162:165], v[166:169], v[78:81]
	v_mfma_f32_16x16x32_bf16 v[70:73], v[162:165], v[170:173], v[70:73]
	v_mfma_f32_16x16x32_bf16 v[66:69], v[162:165], v[192:195], v[66:69]
	v_mfma_f32_16x16x32_bf16 v[58:61], v[162:165], v[196:199], v[58:61]
	ds_read_b128 v[162:165], v0 offset:12288
	s_waitcnt lgkmcnt(0)
	v_mfma_f32_16x16x32_bf16 v[54:57], v[162:165], v[166:169], v[54:57]
	v_mfma_f32_16x16x32_bf16 v[50:53], v[162:165], v[170:173], v[50:53]
	v_mfma_f32_16x16x32_bf16 v[46:49], v[162:165], v[192:195], v[46:49]
	v_mfma_f32_16x16x32_bf16 v[38:41], v[162:165], v[196:199], v[38:41]
	ds_read_b128 v[162:165], v0 offset:14336
	v_add_u32_e32 v0, v0, v190
	s_waitcnt lgkmcnt(0)
	v_mfma_f32_16x16x32_bf16 v[34:37], v[162:165], v[166:169], v[34:37]
	ds_read_b128 v[166:169], v0
	v_mfma_f32_16x16x32_bf16 v[30:33], v[162:165], v[170:173], v[30:33]
	ds_read_b128 v[170:173], v191 offset:2048
	v_mfma_f32_16x16x32_bf16 v[26:29], v[162:165], v[192:195], v[26:29]
	ds_read_b128 v[192:195], v191 offset:4096
	v_mfma_f32_16x16x32_bf16 v[22:25], v[162:165], v[196:199], v[22:25]
	ds_read_b128 v[162:165], v191
	ds_read_b128 v[196:199], v191 offset:6144
	s_waitcnt lgkmcnt(1)
	v_mfma_f32_16x16x32_bf16 v[158:161], v[166:169], v[162:165], v[158:161]
	v_mfma_f32_16x16x32_bf16 v[154:157], v[166:169], v[170:173], v[154:157]
	v_mfma_f32_16x16x32_bf16 v[150:153], v[166:169], v[192:195], v[150:153]
	s_waitcnt lgkmcnt(0)
	v_mfma_f32_16x16x32_bf16 v[146:149], v[166:169], v[196:199], v[146:149]
	ds_read_b128 v[166:169], v0 offset:2048
	s_waitcnt lgkmcnt(0)
	v_mfma_f32_16x16x32_bf16 v[142:145], v[166:169], v[162:165], v[142:145]
	v_mfma_f32_16x16x32_bf16 v[138:141], v[166:169], v[170:173], v[138:141]
	v_mfma_f32_16x16x32_bf16 v[134:137], v[166:169], v[192:195], v[134:137]
	v_mfma_f32_16x16x32_bf16 v[130:133], v[166:169], v[196:199], v[130:133]
	ds_read_b128 v[166:169], v0 offset:4096
	s_waitcnt lgkmcnt(0)
; template <int MI, int NJ> ...
;     ...
;   for (int kt = 0; kt < nk; ++kt) {
;     const int buf = kt & 1;
;     {
;       G8STORE(buf ^ 1);
;       const u16* ga_ = (kt + 2 < nk) ? Ag + (kt + 2) * 64 : Ag + nAoff;
;       const u16* gb_ = (kt + 2 < nk) ? Bg + (kt + 2) * 64 : Bg + nBoff;
;       G8LOADP(ga_, gb_);
;     }
;     __builtin_amdgcn_sched_barrier(0);
;     __builtin_amdgcn_s_setprio(1);
;     const u16* a = ra_ + buf * AROWS * 64;
;     const u16* b = rb_ + buf * BROWS * 64;
; #pragma unroll
;     for (int ks = 0; ks < 2; ++ks) {
;       const u16* a_ = ks ? a + dsw : a;
;       const u16* b_ = ks ? b + dsw : b;
;       bf16x8 bfr[NJ];
; #pragma unroll
;       for (int j = 0; j < NJ; ++j) bfr[j] = *(const bf16x8*)(b_ + j * 16 * 64);
; #pragma unroll
;       for (int ih = 0; ih < MI / 4; ++ih) {
;         bf16x8 af[4];
; #pragma unroll
;         for (int i = 0; i < 4; ++i) af[i] = *(const bf16x8*)(a_ + (ih * 4 + i) * 16 * 64);
; #pragma unroll
;         for (int i = 0; i < 4; ++i)
; #pragma unroll
;           for (int j = 0; j < NJ; ++j) acc[ih * 4 + i][j] = mfma16(af[i], bfr[j], acc[ih * 4 + i][j]);
;       }
;     }
;     __builtin_amdgcn_s_setprio(0);
;     __builtin_amdgcn_sched_barrier(0);
;     __syncthreads();
;   }
	v_mfma_f32_16x16x32_bf16 v[126:129], v[166:169], v[162:165], v[126:129]
	v_mfma_f32_16x16x32_bf16 v[122:125], v[166:169], v[170:173], v[122:125]
	v_mfma_f32_16x16x32_bf16 v[118:121], v[166:169], v[192:195], v[118:121]
	v_mfma_f32_16x16x32_bf16 v[114:117], v[166:169], v[196:199], v[114:117]
	ds_read_b128 v[166:169], v0 offset:6144
	s_waitcnt lgkmcnt(0)
	v_mfma_f32_16x16x32_bf16 v[110:113], v[166:169], v[162:165], v[110:113]
	v_mfma_f32_16x16x32_bf16 v[106:109], v[166:169], v[170:173], v[106:109]
	v_mfma_f32_16x16x32_bf16 v[102:105], v[166:169], v[192:195], v[102:105]
	v_mfma_f32_16x16x32_bf16 v[98:101], v[166:169], v[196:199], v[98:101]
	ds_read_b128 v[166:169], v0 offset:8192
	s_waitcnt lgkmcnt(0)
	v_mfma_f32_16x16x32_bf16 v[94:97], v[166:169], v[162:165], v[94:97]
	v_mfma_f32_16x16x32_bf16 v[90:93], v[166:169], v[170:173], v[90:93]
	v_mfma_f32_16x16x32_bf16 v[86:89], v[166:169], v[192:195], v[86:89]
	v_mfma_f32_16x16x32_bf16 v[82:85], v[166:169], v[196:199], v[82:85]
	ds_read_b128 v[166:169], v0 offset:10240
	s_waitcnt lgkmcnt(0)
	v_mfma_f32_16x16x32_bf16 v[78:81], v[166:169], v[162:165], v[78:81]
	v_mfma_f32_16x16x32_bf16 v[70:73], v[166:169], v[170:173], v[70:73]
	v_mfma_f32_16x16x32_bf16 v[66:69], v[166:169], v[192:195], v[66:69]
	v_mfma_f32_16x16x32_bf16 v[58:61], v[166:169], v[196:199], v[58:61]
	ds_read_b128 v[166:169], v0 offset:12288
	s_waitcnt lgkmcnt(0)
	v_mfma_f32_16x16x32_bf16 v[54:57], v[166:169], v[162:165], v[54:57]
	v_mfma_f32_16x16x32_bf16 v[50:53], v[166:169], v[170:173], v[50:53]
	v_mfma_f32_16x16x32_bf16 v[46:49], v[166:169], v[192:195], v[46:49]
	v_mfma_f32_16x16x32_bf16 v[38:41], v[166:169], v[196:199], v[38:41]
	ds_read_b128 v[166:169], v0 offset:14336
	s_waitcnt lgkmcnt(0)
	v_mfma_f32_16x16x32_bf16 v[34:37], v[166:169], v[162:165], v[34:37]
	v_mfma_f32_16x16x32_bf16 v[30:33], v[166:169], v[170:173], v[30:33]
	v_mfma_f32_16x16x32_bf16 v[26:29], v[166:169], v[192:195], v[26:29]
	v_mfma_f32_16x16x32_bf16 v[22:25], v[166:169], v[196:199], v[22:25]
	s_setprio 0
	s_add_i32 s44, s44, 1
	s_add_i32 s39, s39, 64
	s_addk_i32 s43, 0x4000
	s_barrier
	s_and_b32 s45, s43, 0x4000
	s_xor_b32 s46, s45, 0x4000
	s_lshl_b32 s46, s46, 1
	v_add_u32_e32 v0, s46, v185
	v_add_u32_e32 v191, s46, v186
	s_add_i32 s46, s44, 3
	s_sub_i32 s48, s46, s21
	s_cmp_eq_u32 s48, 1
	s_cselect_b32 s48, 64, 0
	s_add_u32 s49, s13, s48
	s_addc_u32 s50, s12, 0
	s_add_u32 s51, s38, s48
	s_addc_u32 s52, s37, 0
	s_cmp_lt_u32 s46, s21
	s_cselect_b32 s47, 0, s50
	s_cselect_b32 s46, s39, s49
	s_cselect_b32 s53, 0, s52
	s_cselect_b32 s52, s39, s51
	s_waitcnt vmcnt(8)
	ds_write_b128 v0, v[10:13]
	ds_write_b128 v0, v[2:5] offset:8192
	ds_write_b128 v0, v[6:9] offset:16384
	ds_write_b128 v0, v[14:17] offset:24576
	ds_write_b128 v191, v[18:21]
	ds_write_b128 v191, v[42:45] offset:8192
	ds_write_b128 v191, v[62:65] offset:16384
	ds_write_b128 v191, v[74:77] offset:24576
	v_lshl_add_u64 v[242:243], s[46:47], 1, v[180:181]
	v_lshl_add_u64 v[248:249], s[52:53], 1, v[182:183]
	v_lshl_add_u64 v[244:245], v[242:243], 0, s[58:59]
	v_lshl_add_u64 v[250:251], v[248:249], 0, s[58:59]
	global_load_dwordx4 v[10:13], v[242:243], off
	v_lshl_add_u64 v[246:247], v[244:245], 0, s[0:1]
	global_load_dwordx4 v[2:5], v[244:245], off
	v_lshl_add_u64 v[244:245], v[246:247], 0, s[0:1]
	global_load_dwordx4 v[6:9], v[246:247], off
	v_lshl_add_u64 v[228:229], v[250:251], 0, s[0:1]
	global_load_dwordx4 v[14:17], v[244:245], off
	global_load_dwordx4 v[18:21], v[248:249], off
	v_lshl_add_u64 v[246:247], v[228:229], 0, s[0:1]
	global_load_dwordx4 v[42:45], v[250:251], off
	global_load_dwordx4 v[62:65], v[228:229], off
	global_load_dwordx4 v[74:77], v[246:247], off
	s_setprio 1
	s_lshl_b32 s45, s45, 1
	v_add_u32_e32 v0, s45, v187
	v_add_u32_e32 v191, s45, v188
	ds_read_b128 v[162:165], v0
	ds_read_b128 v[166:169], v191
	ds_read_b128 v[170:173], v191 offset:2048
	ds_read_b128 v[192:195], v191 offset:4096
	ds_read_b128 v[196:199], v191 offset:6144
	s_waitcnt lgkmcnt(3)
	v_mfma_f32_16x16x32_bf16 v[158:161], v[162:165], v[166:169], v[158:161]
	v_add_u32_e32 v191, v191, v190
	s_waitcnt lgkmcnt(2)
	v_mfma_f32_16x16x32_bf16 v[154:157], v[162:165], v[170:173], v[154:157]
	s_waitcnt lgkmcnt(1)
	v_mfma_f32_16x16x32_bf16 v[150:153], v[162:165], v[192:195], v[150:153]
	s_waitcnt lgkmcnt(0)
	v_mfma_f32_16x16x32_bf16 v[146:149], v[162:165], v[196:199], v[146:149]
	ds_read_b128 v[162:165], v0 offset:2048
	s_waitcnt lgkmcnt(0)
	v_mfma_f32_16x16x32_bf16 v[142:145], v[162:165], v[166:169], v[142:145]
	v_mfma_f32_16x16x32_bf16 v[138:141], v[162:165], v[170:173], v[138:141]
	v_mfma_f32_16x16x32_bf16 v[134:137], v[162:165], v[192:195], v[134:137]
	v_mfma_f32_16x16x32_bf16 v[130:133], v[162:165], v[196:199], v[130:133]
	ds_read_b128 v[162:165], v0 offset:4096
	s_waitcnt lgkmcnt(0)
	v_mfma_f32_16x16x32_bf16 v[126:129], v[162:165], v[166:169], v[126:129]
	v_mfma_f32_16x16x32_bf16 v[122:125], v[162:165], v[170:173], v[122:125]
	v_mfma_f32_16x16x32_bf16 v[118:121], v[162:165], v[192:195], v[118:121]
	v_mfma_f32_16x16x32_bf16 v[114:117], v[162:165], v[196:199], v[114:117]
	ds_read_b128 v[162:165], v0 offset:6144
	s_waitcnt lgkmcnt(0)
	v_mfma_f32_16x16x32_bf16 v[110:113], v[162:165], v[166:169], v[110:113]
	v_mfma_f32_16x16x32_bf16 v[106:109], v[162:165], v[170:173], v[106:109]
	v_mfma_f32_16x16x32_bf16 v[102:105], v[162:165], v[192:195], v[102:105]
	v_mfma_f32_16x16x32_bf16 v[98:101], v[162:165], v[196:199], v[98:101]
	ds_read_b128 v[162:165], v0 offset:8192
	s_waitcnt lgkmcnt(0)
; template <int MI, int NJ> ...
;     ...
; #pragma unroll
;     for (int ks = 0; ks < 2; ++ks) {
;       const u16* a_ = ks ? a + dsw : a;
;       const u16* b_ = ks ? b + dsw : b;
;       bf16x8 bfr[NJ];
; #pragma unroll
;       for (int j = 0; j < NJ; ++j) bfr[j] = *(const bf16x8*)(b_ + j * 16 * 64);
; #pragma unroll
;       for (int ih = 0; ih < MI / 4; ++ih) {
;         bf16x8 af[4];
; #pragma unroll
;         for (int i = 0; i < 4; ++i) af[i] = *(const bf16x8*)(a_ + (ih * 4 + i) * 16 * 64);
; #pragma unroll
;         for (int i = 0; i < 4; ++i)
; #pragma unroll
;           for (int j = 0; j < NJ; ++j) acc[ih * 4 + i][j] = mfma16(af[i], bfr[j], acc[ih * 4 + i][j]);
;       }
;     }
;     __builtin_amdgcn_s_setprio(0);
;     __builtin_amdgcn_sched_barrier(0);
;     __syncthreads();
;   }
	v_mfma_f32_16x16x32_bf16 v[94:97], v[162:165], v[166:169], v[94:97]
	v_mfma_f32_16x16x32_bf16 v[90:93], v[162:165], v[170:173], v[90:93]
	v_mfma_f32_16x16x32_bf16 v[86:89], v[162:165], v[192:195], v[86:89]
	v_mfma_f32_16x16x32_bf16 v[82:85], v[162:165], v[196:199], v[82:85]
	ds_read_b128 v[162:165], v0 offset:10240
	s_waitcnt lgkmcnt(0)
	v_mfma_f32_16x16x32_bf16 v[78:81], v[162:165], v[166:169], v[78:81]
	v_mfma_f32_16x16x32_bf16 v[70:73], v[162:165], v[170:173], v[70:73]
	v_mfma_f32_16x16x32_bf16 v[66:69], v[162:165], v[192:195], v[66:69]
	v_mfma_f32_16x16x32_bf16 v[58:61], v[162:165], v[196:199], v[58:61]
	ds_read_b128 v[162:165], v0 offset:12288
	s_waitcnt lgkmcnt(0)
	v_mfma_f32_16x16x32_bf16 v[54:57], v[162:165], v[166:169], v[54:57]
	v_mfma_f32_16x16x32_bf16 v[50:53], v[162:165], v[170:173], v[50:53]
	v_mfma_f32_16x16x32_bf16 v[46:49], v[162:165], v[192:195], v[46:49]
	v_mfma_f32_16x16x32_bf16 v[38:41], v[162:165], v[196:199], v[38:41]
	ds_read_b128 v[162:165], v0 offset:14336
	v_add_u32_e32 v0, v0, v190
	s_waitcnt lgkmcnt(0)
	v_mfma_f32_16x16x32_bf16 v[34:37], v[162:165], v[166:169], v[34:37]
	ds_read_b128 v[166:169], v0
	v_mfma_f32_16x16x32_bf16 v[30:33], v[162:165], v[170:173], v[30:33]
	ds_read_b128 v[170:173], v191 offset:2048
	v_mfma_f32_16x16x32_bf16 v[26:29], v[162:165], v[192:195], v[26:29]
	ds_read_b128 v[192:195], v191 offset:4096
	v_mfma_f32_16x16x32_bf16 v[22:25], v[162:165], v[196:199], v[22:25]
	ds_read_b128 v[162:165], v191
	ds_read_b128 v[196:199], v191 offset:6144
	s_waitcnt lgkmcnt(1)
	v_mfma_f32_16x16x32_bf16 v[158:161], v[166:169], v[162:165], v[158:161]
	v_mfma_f32_16x16x32_bf16 v[154:157], v[166:169], v[170:173], v[154:157]
	v_mfma_f32_16x16x32_bf16 v[150:153], v[166:169], v[192:195], v[150:153]
	s_waitcnt lgkmcnt(0)
	v_mfma_f32_16x16x32_bf16 v[146:149], v[166:169], v[196:199], v[146:149]
	ds_read_b128 v[166:169], v0 offset:2048
	s_waitcnt lgkmcnt(0)
	v_mfma_f32_16x16x32_bf16 v[142:145], v[166:169], v[162:165], v[142:145]
	v_mfma_f32_16x16x32_bf16 v[138:141], v[166:169], v[170:173], v[138:141]
	v_mfma_f32_16x16x32_bf16 v[134:137], v[166:169], v[192:195], v[134:137]
	v_mfma_f32_16x16x32_bf16 v[130:133], v[166:169], v[196:199], v[130:133]
	ds_read_b128 v[166:169], v0 offset:4096
	s_waitcnt lgkmcnt(0)
	v_mfma_f32_16x16x32_bf16 v[126:129], v[166:169], v[162:165], v[126:129]
	v_mfma_f32_16x16x32_bf16 v[122:125], v[166:169], v[170:173], v[122:125]
	v_mfma_f32_16x16x32_bf16 v[118:121], v[166:169], v[192:195], v[118:121]
	v_mfma_f32_16x16x32_bf16 v[114:117], v[166:169], v[196:199], v[114:117]
	ds_read_b128 v[166:169], v0 offset:6144
	s_waitcnt lgkmcnt(0)
	v_mfma_f32_16x16x32_bf16 v[110:113], v[166:169], v[162:165], v[110:113]
	v_mfma_f32_16x16x32_bf16 v[106:109], v[166:169], v[170:173], v[106:109]
	v_mfma_f32_16x16x32_bf16 v[102:105], v[166:169], v[192:195], v[102:105]
	v_mfma_f32_16x16x32_bf16 v[98:101], v[166:169], v[196:199], v[98:101]
	ds_read_b128 v[166:169], v0 offset:8192
	s_waitcnt lgkmcnt(0)
	v_mfma_f32_16x16x32_bf16 v[94:97], v[166:169], v[162:165], v[94:97]
	v_mfma_f32_16x16x32_bf16 v[90:93], v[166:169], v[170:173], v[90:93]
	v_mfma_f32_16x16x32_bf16 v[86:89], v[166:169], v[192:195], v[86:89]
	v_mfma_f32_16x16x32_bf16 v[82:85], v[166:169], v[196:199], v[82:85]
	ds_read_b128 v[166:169], v0 offset:10240
	s_waitcnt lgkmcnt(0)
	v_mfma_f32_16x16x32_bf16 v[78:81], v[166:169], v[162:165], v[78:81]
	v_mfma_f32_16x16x32_bf16 v[70:73], v[166:169], v[170:173], v[70:73]
	v_mfma_f32_16x16x32_bf16 v[66:69], v[166:169], v[192:195], v[66:69]
	v_mfma_f32_16x16x32_bf16 v[58:61], v[166:169], v[196:199], v[58:61]
	ds_read_b128 v[166:169], v0 offset:12288
	s_waitcnt lgkmcnt(0)
	v_mfma_f32_16x16x32_bf16 v[54:57], v[166:169], v[162:165], v[54:57]
	v_mfma_f32_16x16x32_bf16 v[50:53], v[166:169], v[170:173], v[50:53]
	v_mfma_f32_16x16x32_bf16 v[46:49], v[166:169], v[192:195], v[46:49]
	v_mfma_f32_16x16x32_bf16 v[38:41], v[166:169], v[196:199], v[38:41]
	ds_read_b128 v[166:169], v0 offset:14336
	s_waitcnt lgkmcnt(0)
	v_mfma_f32_16x16x32_bf16 v[34:37], v[166:169], v[162:165], v[34:37]
	v_mfma_f32_16x16x32_bf16 v[30:33], v[166:169], v[170:173], v[30:33]
	v_mfma_f32_16x16x32_bf16 v[26:29], v[166:169], v[192:195], v[26:29]
	v_mfma_f32_16x16x32_bf16 v[22:25], v[166:169], v[196:199], v[22:25]
	s_setprio 0
	s_add_i32 s44, s44, 1
	s_add_i32 s39, s39, 64
	s_addk_i32 s43, 0x4000
	s_cmp_lg_u32 s21, s44
	s_barrier
	s_cbranch_scc1 .LBB0_481
; __device__ __forceinline__ void phase_gemm_f32(const u16* A, const u16* Bt, int K, u16* out, u16* smem,
;                                                volatile LAS unsigned* vb_) {
;     ...
; #pragma unroll
;     for (int i = 0; i < 8; ++i)
; #pragma unroll
;       for (int j = 0; j < 4; ++j)
; #pragma unroll
;         for (int r = 0; r < 4; ++r)
;           smem[(wm * 128 + i * 16 + (lane >> 4) * 4 + r) * 264 + wn * 64 + j * 16 + (lane & 15)] = f2bf(acc[i][j][r]);
;     __syncthreads();
	v_cvt_pk_bf16_f32 v0, v158, s0
	ds_write_b16 v189, v0
	v_cvt_pk_bf16_f32 v0, v159, s0
	ds_write_b16 v189, v0 offset:528
	v_cvt_pk_bf16_f32 v0, v160, s0
	ds_write_b16 v189, v0 offset:1056
	v_cvt_pk_bf16_f32 v0, v161, s0
	ds_write_b16 v189, v0 offset:1584
	v_cvt_pk_bf16_f32 v0, v154, s0
	ds_write_b16 v189, v0 offset:32
	v_cvt_pk_bf16_f32 v0, v155, s0
	ds_write_b16 v189, v0 offset:560
	v_cvt_pk_bf16_f32 v0, v156, s0
	ds_write_b16 v189, v0 offset:1088
	v_cvt_pk_bf16_f32 v0, v157, s0
	ds_write_b16 v189, v0 offset:1616
	v_cvt_pk_bf16_f32 v0, v150, s0
	ds_write_b16 v189, v0 offset:64
	v_cvt_pk_bf16_f32 v0, v151, s0
	ds_write_b16 v189, v0 offset:592
	v_cvt_pk_bf16_f32 v0, v152, s0
	ds_write_b16 v189, v0 offset:1120
	v_cvt_pk_bf16_f32 v0, v153, s0
	ds_write_b16 v189, v0 offset:1648
	v_cvt_pk_bf16_f32 v0, v146, s0
	ds_write_b16 v189, v0 offset:96
	v_cvt_pk_bf16_f32 v0, v147, s0
	ds_write_b16 v189, v0 offset:624
	v_cvt_pk_bf16_f32 v0, v148, s0
	ds_write_b16 v189, v0 offset:1152
	v_cvt_pk_bf16_f32 v0, v149, s0
	ds_write_b16 v189, v0 offset:1680
	v_cvt_pk_bf16_f32 v0, v142, s0
	ds_write_b16 v189, v0 offset:8448
	v_cvt_pk_bf16_f32 v0, v143, s0
	ds_write_b16 v189, v0 offset:8976
	v_cvt_pk_bf16_f32 v0, v144, s0
	ds_write_b16 v189, v0 offset:9504
	v_cvt_pk_bf16_f32 v0, v145, s0
	ds_write_b16 v189, v0 offset:10032
	v_cvt_pk_bf16_f32 v0, v138, s0
	ds_write_b16 v189, v0 offset:8480
	v_cvt_pk_bf16_f32 v0, v139, s0
	ds_write_b16 v189, v0 offset:9008
	v_cvt_pk_bf16_f32 v0, v140, s0
	ds_write_b16 v189, v0 offset:9536
	v_cvt_pk_bf16_f32 v0, v141, s0
	ds_write_b16 v189, v0 offset:10064
	v_cvt_pk_bf16_f32 v0, v134, s0
	ds_write_b16 v189, v0 offset:8512
	v_cvt_pk_bf16_f32 v0, v135, s0
	ds_write_b16 v189, v0 offset:9040
	v_cvt_pk_bf16_f32 v0, v136, s0
	ds_write_b16 v189, v0 offset:9568
	v_cvt_pk_bf16_f32 v0, v137, s0
	ds_write_b16 v189, v0 offset:10096
	v_cvt_pk_bf16_f32 v0, v130, s0
	ds_write_b16 v189, v0 offset:8544
	v_cvt_pk_bf16_f32 v0, v131, s0
	ds_write_b16 v189, v0 offset:9072
	v_cvt_pk_bf16_f32 v0, v132, s0
	ds_write_b16 v189, v0 offset:9600
	v_cvt_pk_bf16_f32 v0, v133, s0
	ds_write_b16 v189, v0 offset:10128
	v_cvt_pk_bf16_f32 v0, v126, s0
	ds_write_b16 v189, v0 offset:16896
	v_cvt_pk_bf16_f32 v0, v127, s0
	ds_write_b16 v189, v0 offset:17424
	v_cvt_pk_bf16_f32 v0, v128, s0
	ds_write_b16 v189, v0 offset:17952
	v_cvt_pk_bf16_f32 v0, v129, s0
	ds_write_b16 v189, v0 offset:18480
	v_cvt_pk_bf16_f32 v0, v122, s0
	ds_write_b16 v189, v0 offset:16928
	v_cvt_pk_bf16_f32 v0, v123, s0
	ds_write_b16 v189, v0 offset:17456
	v_cvt_pk_bf16_f32 v0, v124, s0
	ds_write_b16 v189, v0 offset:17984
	v_cvt_pk_bf16_f32 v0, v125, s0
	ds_write_b16 v189, v0 offset:18512
	v_cvt_pk_bf16_f32 v0, v118, s0
	ds_write_b16 v189, v0 offset:16960
	v_cvt_pk_bf16_f32 v0, v119, s0
	ds_write_b16 v189, v0 offset:17488
	v_cvt_pk_bf16_f32 v0, v120, s0
	ds_write_b16 v189, v0 offset:18016
	v_cvt_pk_bf16_f32 v0, v121, s0
	ds_write_b16 v189, v0 offset:18544
	v_cvt_pk_bf16_f32 v0, v114, s0
	ds_write_b16 v189, v0 offset:16992
	v_cvt_pk_bf16_f32 v0, v115, s0
	ds_write_b16 v189, v0 offset:17520
	v_cvt_pk_bf16_f32 v0, v116, s0
	ds_write_b16 v189, v0 offset:18048
	v_cvt_pk_bf16_f32 v0, v117, s0
	ds_write_b16 v189, v0 offset:18576
	v_cvt_pk_bf16_f32 v0, v110, s0
	ds_write_b16 v189, v0 offset:25344
	v_cvt_pk_bf16_f32 v0, v111, s0
	ds_write_b16 v189, v0 offset:25872
	v_cvt_pk_bf16_f32 v0, v112, s0
	ds_write_b16 v189, v0 offset:26400
	v_cvt_pk_bf16_f32 v0, v113, s0
	ds_write_b16 v189, v0 offset:26928
	v_cvt_pk_bf16_f32 v0, v106, s0
	ds_write_b16 v189, v0 offset:25376
	v_cvt_pk_bf16_f32 v0, v107, s0
	ds_write_b16 v189, v0 offset:25904
	v_cvt_pk_bf16_f32 v0, v108, s0
	ds_write_b16 v189, v0 offset:26432
	v_cvt_pk_bf16_f32 v0, v109, s0
	ds_write_b16 v189, v0 offset:26960
	v_cvt_pk_bf16_f32 v0, v102, s0
	ds_write_b16 v189, v0 offset:25408
	v_cvt_pk_bf16_f32 v0, v103, s0
	ds_write_b16 v189, v0 offset:25936
	v_cvt_pk_bf16_f32 v0, v104, s0
	ds_write_b16 v189, v0 offset:26464
	v_cvt_pk_bf16_f32 v0, v105, s0
	ds_write_b16 v189, v0 offset:26992
	v_cvt_pk_bf16_f32 v0, v98, s0
	ds_write_b16 v189, v0 offset:25440
	v_cvt_pk_bf16_f32 v0, v99, s0
	ds_write_b16 v189, v0 offset:25968
	v_cvt_pk_bf16_f32 v0, v100, s0
	ds_write_b16 v189, v0 offset:26496
	v_cvt_pk_bf16_f32 v0, v101, s0
	ds_write_b16 v189, v0 offset:27024
	v_cvt_pk_bf16_f32 v0, v94, s0
	ds_write_b16 v189, v0 offset:33792
	v_cvt_pk_bf16_f32 v0, v95, s0
	ds_write_b16 v189, v0 offset:34320
	v_cvt_pk_bf16_f32 v0, v96, s0
	ds_write_b16 v189, v0 offset:34848
	v_cvt_pk_bf16_f32 v0, v97, s0
	ds_write_b16 v189, v0 offset:35376
	v_cvt_pk_bf16_f32 v0, v90, s0
	ds_write_b16 v189, v0 offset:33824
	v_cvt_pk_bf16_f32 v0, v91, s0
	ds_write_b16 v189, v0 offset:34352
	v_cvt_pk_bf16_f32 v0, v92, s0
	ds_write_b16 v189, v0 offset:34880
	v_cvt_pk_bf16_f32 v0, v93, s0
	ds_write_b16 v189, v0 offset:35408
	v_cvt_pk_bf16_f32 v0, v86, s0
	ds_write_b16 v189, v0 offset:33856
	v_cvt_pk_bf16_f32 v0, v87, s0
	ds_write_b16 v189, v0 offset:34384
	v_cvt_pk_bf16_f32 v0, v88, s0
	ds_write_b16 v189, v0 offset:34912
	v_cvt_pk_bf16_f32 v0, v89, s0
	ds_write_b16 v189, v0 offset:35440
	v_cvt_pk_bf16_f32 v0, v82, s0
	ds_write_b16 v189, v0 offset:33888
	v_cvt_pk_bf16_f32 v0, v83, s0
	ds_write_b16 v189, v0 offset:34416
	v_cvt_pk_bf16_f32 v0, v84, s0
	ds_write_b16 v189, v0 offset:34944
	v_cvt_pk_bf16_f32 v0, v85, s0
	ds_write_b16 v189, v0 offset:35472
	v_cvt_pk_bf16_f32 v0, v78, s0
	ds_write_b16 v189, v0 offset:42240
	v_cvt_pk_bf16_f32 v0, v79, s0
	ds_write_b16 v189, v0 offset:42768
	v_cvt_pk_bf16_f32 v0, v80, s0
	ds_write_b16 v189, v0 offset:43296
	v_cvt_pk_bf16_f32 v0, v81, s0
	ds_write_b16 v189, v0 offset:43824
; __device__ __forceinline__ void phase_gemm_f32(const u16* A, const u16* Bt, int K, u16* out, u16* smem,
;                                                volatile LAS unsigned* vb_) {
;     ...
; #pragma unroll
;     for (int i = 0; i < 8; ++i)
; #pragma unroll
;       for (int j = 0; j < 4; ++j)
; #pragma unroll
;         for (int r = 0; r < 4; ++r)
;           smem[(wm * 128 + i * 16 + (lane >> 4) * 4 + r) * 264 + wn * 64 + j * 16 + (lane & 15)] = f2bf(acc[i][j][r]);
;     __syncthreads();
	v_cvt_pk_bf16_f32 v0, v70, s0
	ds_write_b16 v189, v0 offset:42272
	v_cvt_pk_bf16_f32 v0, v71, s0
	ds_write_b16 v189, v0 offset:42800
	v_cvt_pk_bf16_f32 v0, v72, s0
	ds_write_b16 v189, v0 offset:43328
	v_cvt_pk_bf16_f32 v0, v73, s0
	ds_write_b16 v189, v0 offset:43856
	v_cvt_pk_bf16_f32 v0, v66, s0
	ds_write_b16 v189, v0 offset:42304
	v_cvt_pk_bf16_f32 v0, v67, s0
	ds_write_b16 v189, v0 offset:42832
	v_cvt_pk_bf16_f32 v0, v68, s0
	ds_write_b16 v189, v0 offset:43360
	v_cvt_pk_bf16_f32 v0, v69, s0
	ds_write_b16 v189, v0 offset:43888
	v_cvt_pk_bf16_f32 v0, v58, s0
	ds_write_b16 v189, v0 offset:42336
	v_cvt_pk_bf16_f32 v0, v59, s0
	ds_write_b16 v189, v0 offset:42864
	v_cvt_pk_bf16_f32 v0, v60, s0
	ds_write_b16 v189, v0 offset:43392
	v_cvt_pk_bf16_f32 v0, v61, s0
	ds_write_b16 v189, v0 offset:43920
	v_cvt_pk_bf16_f32 v0, v54, s0
	ds_write_b16 v189, v0 offset:50688
	v_cvt_pk_bf16_f32 v0, v55, s0
	ds_write_b16 v189, v0 offset:51216
	v_cvt_pk_bf16_f32 v0, v56, s0
	ds_write_b16 v189, v0 offset:51744
	v_cvt_pk_bf16_f32 v0, v57, s0
	ds_write_b16 v189, v0 offset:52272
	v_cvt_pk_bf16_f32 v0, v50, s0
	ds_write_b16 v189, v0 offset:50720
	v_cvt_pk_bf16_f32 v0, v51, s0
	ds_write_b16 v189, v0 offset:51248
	v_cvt_pk_bf16_f32 v0, v52, s0
	ds_write_b16 v189, v0 offset:51776
	v_cvt_pk_bf16_f32 v0, v53, s0
	ds_write_b16 v189, v0 offset:52304
	v_cvt_pk_bf16_f32 v0, v46, s0
	ds_write_b16 v189, v0 offset:50752
	v_cvt_pk_bf16_f32 v0, v47, s0
	ds_write_b16 v189, v0 offset:51280
	v_cvt_pk_bf16_f32 v0, v48, s0
	ds_write_b16 v189, v0 offset:51808
	v_cvt_pk_bf16_f32 v0, v49, s0
	ds_write_b16 v189, v0 offset:52336
	v_cvt_pk_bf16_f32 v0, v38, s0
	ds_write_b16 v189, v0 offset:50784
	v_cvt_pk_bf16_f32 v0, v39, s0
	ds_write_b16 v189, v0 offset:51312
	v_cvt_pk_bf16_f32 v0, v40, s0
	ds_write_b16 v189, v0 offset:51840
	v_cvt_pk_bf16_f32 v0, v41, s0
	ds_write_b16 v189, v0 offset:52368
	v_cvt_pk_bf16_f32 v0, v34, s0
	ds_write_b16 v189, v0 offset:59136
	v_cvt_pk_bf16_f32 v0, v35, s0
	ds_write_b16 v189, v0 offset:59664
	v_cvt_pk_bf16_f32 v0, v36, s0
	ds_write_b16 v189, v0 offset:60192
	v_cvt_pk_bf16_f32 v0, v37, s0
	ds_write_b16 v189, v0 offset:60720
	v_cvt_pk_bf16_f32 v0, v30, s0
	ds_write_b16 v189, v0 offset:59168
	v_cvt_pk_bf16_f32 v0, v31, s0
	ds_write_b16 v189, v0 offset:59696
	v_cvt_pk_bf16_f32 v0, v32, s0
	ds_write_b16 v189, v0 offset:60224
	v_cvt_pk_bf16_f32 v0, v33, s0
	ds_write_b16 v189, v0 offset:60752
	v_cvt_pk_bf16_f32 v0, v26, s0
	ds_write_b16 v189, v0 offset:59200
	v_cvt_pk_bf16_f32 v0, v27, s0
	ds_write_b16 v189, v0 offset:59728
	v_cvt_pk_bf16_f32 v0, v28, s0
	ds_write_b16 v189, v0 offset:60256
	v_cvt_pk_bf16_f32 v0, v29, s0
	ds_write_b16 v189, v0 offset:60784
	v_cvt_pk_bf16_f32 v0, v22, s0
	ds_write_b16 v189, v0 offset:59232
	v_cvt_pk_bf16_f32 v0, v23, s0
	ds_write_b16 v189, v0 offset:59760
	v_cvt_pk_bf16_f32 v0, v24, s0
	s_ashr_i32 s43, s42, 31
	ds_write_b16 v189, v0 offset:60288
	v_cvt_pk_bf16_f32 v0, v25, s0
	v_mov_b32_e32 v34, v175
	s_lshl_b64 s[12:13], s[42:43], 1
	ds_write_b16 v189, v0 offset:60816
	s_waitcnt lgkmcnt(0)
	s_barrier
; #define RTID opaque_tid()
; __device__ __forceinline__ void phase_gemm_f32(const u16* A, const u16* Bt, int K, u16* out, u16* smem,
;                                                volatile LAS unsigned* vb_) {
;     ...
;     const int tid2 = RTID;
; #pragma unroll
;     for (int k = 0; k < 16; ++k) {
;       const int c = tid2 + 512 * k;
;       const int row = c >> 5, ch = c & 31;
;       const uint4 v = *(const uint4*)(smem + row * 264 + ch * 8);
;       *(uint4*)(out + (size_t)(mt * 256 + row) * 1024 + nt * 256 + ch * 8) = v;
;     }
;     __syncthreads();
;   }
	s_add_u32 s12, s11, s12
	v_lshlrev_b32_e32 v0, 4, v34
	v_and_b32_e32 v0, 0x1f0, v0
	s_addc_u32 s13, s20, s13
	v_ashrrev_i32_e32 v26, 5, v34
	v_lshl_add_u64 v[30:31], s[12:13], 0, v[0:1]
	v_mad_u64_u32 v[22:23], s[12:13], v26, s2, v[0:1]
	v_add_u32_e32 v26, s23, v26
	v_ashrrev_i32_e32 v27, 31, v26
	ds_read_b128 v[22:25], v22
	v_lshlrev_b64 v[26:27], 11, v[26:27]
	v_lshl_add_u64 v[32:33], v[30:31], 0, v[26:27]
	v_add_u32_e32 v26, 0x200, v34
	v_ashrrev_i32_e32 v35, 5, v26
	v_mad_u64_u32 v[26:27], s[12:13], v35, s2, v[0:1]
	ds_read_b128 v[26:29], v26
	s_waitcnt lgkmcnt(1)
	global_store_dwordx4 v[32:33], v[22:25], off
	s_and_b64 vcc, exec, s[40:41]
	s_mov_b32 s37, s36
	v_add_u32_e32 v22, s23, v35
	v_ashrrev_i32_e32 v23, 31, v22
	v_lshlrev_b64 v[22:23], 11, v[22:23]
	v_lshl_add_u64 v[22:23], v[30:31], 0, v[22:23]
	s_waitcnt lgkmcnt(0)
	global_store_dwordx4 v[22:23], v[26:29], off
	v_add_u32_e32 v22, 0x400, v34
	s_nop 0
	v_ashrrev_i32_e32 v26, 5, v22
	v_mad_u64_u32 v[22:23], s[12:13], v26, s2, v[0:1]
	v_add_u32_e32 v26, s23, v26
	v_ashrrev_i32_e32 v27, 31, v26
	ds_read_b128 v[22:25], v22
	v_lshlrev_b64 v[26:27], 11, v[26:27]
	v_lshl_add_u64 v[32:33], v[30:31], 0, v[26:27]
	v_add_u32_e32 v26, 0x600, v34
	v_ashrrev_i32_e32 v35, 5, v26
	v_mad_u64_u32 v[26:27], s[12:13], v35, s2, v[0:1]
	ds_read_b128 v[26:29], v26
	s_waitcnt lgkmcnt(1)
	global_store_dwordx4 v[32:33], v[22:25], off
	s_nop 1
	v_add_u32_e32 v22, s23, v35
	v_ashrrev_i32_e32 v23, 31, v22
	v_lshlrev_b64 v[22:23], 11, v[22:23]
	v_lshl_add_u64 v[22:23], v[30:31], 0, v[22:23]
	s_waitcnt lgkmcnt(0)
	global_store_dwordx4 v[22:23], v[26:29], off
	v_add_u32_e32 v22, 0x800, v34
	s_nop 0
	v_ashrrev_i32_e32 v26, 5, v22
	v_mad_u64_u32 v[22:23], s[12:13], v26, s2, v[0:1]
	v_add_u32_e32 v26, s23, v26
	v_ashrrev_i32_e32 v27, 31, v26
	ds_read_b128 v[22:25], v22
	v_lshlrev_b64 v[26:27], 11, v[26:27]
	v_lshl_add_u64 v[32:33], v[30:31], 0, v[26:27]
	v_add_u32_e32 v26, 0xa00, v34
	v_ashrrev_i32_e32 v35, 5, v26
	v_mad_u64_u32 v[26:27], s[12:13], v35, s2, v[0:1]
	ds_read_b128 v[26:29], v26
	s_waitcnt lgkmcnt(1)
	global_store_dwordx4 v[32:33], v[22:25], off
	s_nop 1
	v_add_u32_e32 v22, s23, v35
	v_ashrrev_i32_e32 v23, 31, v22
	v_lshlrev_b64 v[22:23], 11, v[22:23]
	v_lshl_add_u64 v[22:23], v[30:31], 0, v[22:23]
	s_waitcnt lgkmcnt(0)
	global_store_dwordx4 v[22:23], v[26:29], off
	v_add_u32_e32 v22, 0xc00, v34
	s_nop 0
	v_ashrrev_i32_e32 v26, 5, v22
	v_mad_u64_u32 v[22:23], s[12:13], v26, s2, v[0:1]
	v_add_u32_e32 v26, s23, v26
	v_ashrrev_i32_e32 v27, 31, v26
	ds_read_b128 v[22:25], v22
	v_lshlrev_b64 v[26:27], 11, v[26:27]
	v_lshl_add_u64 v[32:33], v[30:31], 0, v[26:27]
	v_add_u32_e32 v26, 0xe00, v34
	v_ashrrev_i32_e32 v35, 5, v26
	v_mad_u64_u32 v[26:27], s[12:13], v35, s2, v[0:1]
	ds_read_b128 v[26:29], v26
	s_waitcnt lgkmcnt(1)
	global_store_dwordx4 v[32:33], v[22:25], off
	s_nop 1
	v_add_u32_e32 v22, s23, v35
	v_ashrrev_i32_e32 v23, 31, v22
	v_lshlrev_b64 v[22:23], 11, v[22:23]
	v_lshl_add_u64 v[22:23], v[30:31], 0, v[22:23]
	s_waitcnt lgkmcnt(0)
	global_store_dwordx4 v[22:23], v[26:29], off
	v_add_u32_e32 v22, 0x1000, v34
	s_nop 0
	v_ashrrev_i32_e32 v26, 5, v22
	v_mad_u64_u32 v[22:23], s[12:13], v26, s2, v[0:1]
	v_add_u32_e32 v26, s23, v26
	v_ashrrev_i32_e32 v27, 31, v26
	ds_read_b128 v[22:25], v22
	v_lshlrev_b64 v[26:27], 11, v[26:27]
	v_lshl_add_u64 v[32:33], v[30:31], 0, v[26:27]
	v_add_u32_e32 v26, 0x1200, v34
	v_ashrrev_i32_e32 v35, 5, v26
	v_mad_u64_u32 v[26:27], s[12:13], v35, s2, v[0:1]
	ds_read_b128 v[26:29], v26
	s_waitcnt lgkmcnt(1)
	global_store_dwordx4 v[32:33], v[22:25], off
	s_nop 1
	v_add_u32_e32 v22, s23, v35
	v_ashrrev_i32_e32 v23, 31, v22
	v_lshlrev_b64 v[22:23], 11, v[22:23]
	v_lshl_add_u64 v[22:23], v[30:31], 0, v[22:23]
	s_waitcnt lgkmcnt(0)
	global_store_dwordx4 v[22:23], v[26:29], off
	v_add_u32_e32 v22, 0x1400, v34
	s_nop 0
	v_ashrrev_i32_e32 v26, 5, v22
	v_mad_u64_u32 v[22:23], s[12:13], v26, s2, v[0:1]
	v_add_u32_e32 v26, s23, v26
	v_ashrrev_i32_e32 v27, 31, v26
	ds_read_b128 v[22:25], v22
	v_lshlrev_b64 v[26:27], 11, v[26:27]
	v_lshl_add_u64 v[32:33], v[30:31], 0, v[26:27]
	v_add_u32_e32 v26, 0x1600, v34
	v_ashrrev_i32_e32 v35, 5, v26
	v_mad_u64_u32 v[26:27], s[12:13], v35, s2, v[0:1]
	ds_read_b128 v[26:29], v26
	s_waitcnt lgkmcnt(1)
	global_store_dwordx4 v[32:33], v[22:25], off
	s_nop 1
	v_add_u32_e32 v22, s23, v35
	v_ashrrev_i32_e32 v23, 31, v22
	v_lshlrev_b64 v[22:23], 11, v[22:23]
	v_lshl_add_u64 v[22:23], v[30:31], 0, v[22:23]
	s_waitcnt lgkmcnt(0)
	global_store_dwordx4 v[22:23], v[26:29], off
	v_add_u32_e32 v22, 0x1800, v34
	s_nop 0
	v_ashrrev_i32_e32 v26, 5, v22
	v_mad_u64_u32 v[22:23], s[12:13], v26, s2, v[0:1]
	v_add_u32_e32 v26, s23, v26
	v_ashrrev_i32_e32 v27, 31, v26
	ds_read_b128 v[22:25], v22
	v_lshlrev_b64 v[26:27], 11, v[26:27]
	v_lshl_add_u64 v[32:33], v[30:31], 0, v[26:27]
	v_add_u32_e32 v26, 0x1a00, v34
	v_ashrrev_i32_e32 v35, 5, v26
	v_mad_u64_u32 v[26:27], s[12:13], v35, s2, v[0:1]
	ds_read_b128 v[26:29], v26
	s_waitcnt lgkmcnt(1)
	global_store_dwordx4 v[32:33], v[22:25], off
	s_nop 1
	v_add_u32_e32 v22, s23, v35
	v_ashrrev_i32_e32 v23, 31, v22
	v_lshlrev_b64 v[22:23], 11, v[22:23]
	v_lshl_add_u64 v[22:23], v[30:31], 0, v[22:23]
	s_waitcnt lgkmcnt(0)
	global_store_dwordx4 v[22:23], v[26:29], off
	v_add_u32_e32 v22, 0x1c00, v34
	s_nop 0
	v_ashrrev_i32_e32 v26, 5, v22
	v_mad_u64_u32 v[22:23], s[12:13], v26, s2, v[0:1]
	v_add_u32_e32 v26, s23, v26
	v_ashrrev_i32_e32 v27, 31, v26
	ds_read_b128 v[22:25], v22
	v_lshlrev_b64 v[26:27], 11, v[26:27]
	v_lshl_add_u64 v[32:33], v[30:31], 0, v[26:27]
	v_add_u32_e32 v26, 0x1e00, v34
	v_ashrrev_i32_e32 v34, 5, v26
	v_mad_u64_u32 v[26:27], s[12:13], v34, s2, v[0:1]
	ds_read_b128 v[26:29], v26
	s_waitcnt lgkmcnt(1)
	global_store_dwordx4 v[32:33], v[22:25], off
	s_mov_b64 s[12:13], -1
	s_nop 0
	v_add_u32_e32 v22, s23, v34
	v_ashrrev_i32_e32 v23, 31, v22
	v_lshlrev_b64 v[22:23], 11, v[22:23]
	v_lshl_add_u64 v[22:23], v[30:31], 0, v[22:23]
	s_waitcnt lgkmcnt(0)
	global_store_dwordx4 v[22:23], v[26:29], off
	s_barrier
	s_cbranch_vccz .LBB0_478
.LBB0_483:
	s_waitcnt vmcnt(0)
	s_mov_b64 s[0:1], 0
	v_writelane_b32 v255, s0, 2
	s_nop 1
	v_writelane_b32 v255, s1, 3

; __device__ __forceinline__ unsigned xb_ld(unsigned* p)              { return __hip_atomic_load(p, __ATOMIC_RELAXED, __HIP_MEMORY_SCOPE_AGENT); }
; __device__ __forceinline__ unsigned xb_add(unsigned* p, unsigned v) { return __hip_atomic_fetch_add(p, v, __ATOMIC_RELAXED, __HIP_MEMORY_SCOPE_AGENT); }
; #define XB_SPIN(cond, bar) do { unsigned _sp = 0; while (cond) { __builtin_amdgcn_s_sleep(1); \
;     if ((++_sp & 255u) == 0u) { if (xb_ld(&(bar)[XB_TMO])) break; if (_sp > XB_SPIN_CAP) { atomicAdd(&(bar)[XB_TMO], 1u); break; } } } } while (0)
; __device__ __forceinline__ void xcd_barrier(const XcdBarrier& b) {
;     asm volatile("s_waitcnt vmcnt(0)" ::: "memory");
;     __syncthreads();
;     if (threadIdx.x == 0) {
;         unsigned* bar = b.bar;
;         __builtin_amdgcn_s_waitcnt(0);
;         unsigned nloc = b.st[0], nx = b.st[1];
;         if (nloc == 0u) { xcd_barrier_complete(bar, b.x, nloc, nx); b.st[0] = nloc; b.st[1] = nx; }
;         const unsigned old = xb_add(&bar[XB_XSUB(b.x)], 1u);
;         const unsigned gen = old / nloc;
;         if (old + 1u == (gen + 1u) * nloc) {
;             __builtin_amdgcn_fence(__ATOMIC_RELEASE, "agent");
;             asm volatile("s_waitcnt vmcnt(0)" ::: "memory");
;             const unsigned og = xb_add(&bar[XB_TOP], 1u);
;             const unsigned tg = og / nx;
;             if (og + 1u == (tg + 1u) * nx) xb_add(&bar[XB_TOPGEN], 1u);
;             else XB_SPIN(xb_ld(&bar[XB_TOPGEN]) == tg, bar);
;             __builtin_amdgcn_fence(__ATOMIC_ACQUIRE, "agent");
;             xb_add(&bar[XB_XGEN(b.x)], 1u);
;             asm volatile("s_waitcnt vmcnt(0)" ::: "memory");
;         } else {
;             XB_SPIN(xb_ld(&bar[XB_XGEN(b.x)]) == gen, bar);
;             __builtin_amdgcn_fence(__ATOMIC_ACQUIRE, "agent");
;             asm volatile("s_waitcnt vmcnt(0)" ::: "memory");
;         }
;     }
;     __syncthreads();
; }
; __global__ void __launch_bounds__(512, 2) mega(Params p) {
;     ...
;     else if (gs < 59) xcd_barrier(xb);
.LBB0_641:
	s_or_b64 exec, exec, s[0:1]
	s_mov_b64 s[10:11], -1
	s_waitcnt lgkmcnt(0)
	s_barrier
.LBB0_642:
	s_branch .Ltramp7
.LBB0_644:
	s_andn2_b64 vcc, exec, s[12:13]
	s_cbranch_vccz .LBB0_648
	s_mov_b64 s[20:21], exec
	v_mbcnt_lo_u32_b32 v17, s20, 0
	v_mbcnt_hi_u32_b32 v17, s21, v17
	v_cmp_eq_u32_e32 vcc, 0, v17
	s_and_saveexec_b64 s[12:13], vcc
	s_cbranch_execz .LBB0_647
	s_bcnt1_i32_b64 s20, s[20:21]
	v_mov_b32_e32 v17, s20
	v_readlane_b32 s20, v253, 10
	v_readlane_b32 s21, v253, 11
	s_nop 4
	global_atomic_add v1, v17, s[20:21]
